# attention: workgroups with bid bit 3 set take their first queue ticket ~3 us later (dynamic queue, no work lost) so the two halves alternate load / compute phases
# speedup vs baseline: 1.0078x; 1.0021x over previous
.LBB0_1130:
	s_bitcmp0_b32 s2, 3
	s_cbranch_scc1 .Lg4d_skip
	s_sleep 100
